# v11 + windowed attention loops: mask code made contiguous after the QK MFMAs, skipped for tiles fully inside the window (wave-uniform test)
# speedup vs baseline: 1.0140x; 1.0106x over previous
; DI s16x4 vtr(const LAS unsigned char* p) { return __builtin_bit_cast(s16x4, __builtin_amdgcn_ds_read_tr16_b64_v4i16((LAS s16x4*)p)); }
; template <int DQK, bool WIN>
; DI void attn_run(int wv, const bf16_t* Qrow0, int qs, const bf16_t* Kb, int ks, const bf16_t* Vb, int vs,
;                  int kt0, int kt1, int qpos0, int window, LAS unsigned char* lds, f32x16 (&o)[2], float& m_out, float& l_out) {
;     ...
;             f32x16 p0 = __builtin_amdgcn_mfma_f32_32x32x16_bf16(kf0[0], q[0], negm, 0, 0, 0);
;             f32x16 p1 = __builtin_amdgcn_mfma_f32_32x32x16_bf16(kf1[0], q[0], negm, 0, 0, 0);
; #pragma unroll
;             for (int ds = 1; ds < NDS; ++ds) {
;                 p0 = __builtin_amdgcn_mfma_f32_32x32x16_bf16(kf0[ds], q[ds], p0, 0, 0, 0);
;                 p1 = __builtin_amdgcn_mfma_f32_32x32x16_bf16(kf1[ds], q[ds], p1, 0, 0, 0);
;             }
;             __builtin_amdgcn_s_setprio(0);
;             s16x4 vlo[4][2], vhi[4][2];
; #pragma unroll
;             for (int k4 = 0; k4 < 4; ++k4)
; #pragma unroll
;                 for (int db = 0; db < 2; ++db) {
;                     vlo[k4][db] = vtr(base + vfo + (16 * k4) * VP + 64 * db);
;                     vhi[k4][db] = vtr(base + vfo + (16 * k4 + 8) * VP + 64 * db);
;                 }
;             if (WIN) {
;                 const int qp_ = qpos0 + r32, kb_ = 64 * kt + 4 * h;
; #pragma unroll
;                 for (int r = 0; r < 16; ++r) {
;                     const int kk = kb_ + (r & 3) + 8 * (r >> 2);
;                     int d0 = qp_ - kk; d0 = d0 < 0 ? -d0 : d0;
;                     int d1 = qp_ - kk - 32; d1 = d1 < 0 ? -d1 : d1;
;                     if (d0 > window) p0[r] = -1e30f;
;                     if (d1 > window) p1[r] = -1e30f;
;                 }
.LBB0_1246:
	s_add_i32 s26, s44, s13
	s_sub_i32 vcc_hi, s26, 64
	s_add_i32 m0, s34, 31
	s_cmp_ge_i32 vcc_hi, m0
	s_cselect_b32 m0, 1, 0
	s_sub_i32 vcc_lo, s35, 0x5e
	s_cmp_le_i32 vcc_hi, vcc_lo
	s_cselect_b32 vcc_lo, 1, 0
	s_and_b32 m0, m0, vcc_lo
	s_and_b32 s15, s12, 1
	s_sub_i32 s28, s26, 64
	s_add_i32 s26, s26, -1
	s_cmp_ge_i32 s26, s34
	s_cselect_b64 s[26:27], -1, 0
	s_cmp_le_i32 s28, s35
	s_cselect_b64 s[28:29], -1, 0
	s_and_b64 s[26:27], s[26:27], s[28:29]
	s_andn2_b64 vcc, exec, s[26:27]
	s_cbranch_vccnz .LBB0_1255
	s_mul_i32 s26, s15, 0x5400
	s_add_i32 s28, s26, 0
	v_add3_u32 v52, s28, v154, v144
	ds_read_b128 v[48:51], v52
	ds_read_b128 v[112:115], v52 offset:32
	ds_read_b128 v[116:119], v52 offset:4608
	ds_read_b128 v[120:123], v52 offset:4640
	ds_read_b128 v[124:127], v52 offset:64
	ds_read_b128 v[146:149], v52 offset:96
	ds_read_b128 v[162:165], v52 offset:4672
	ds_read_b128 v[166:169], v52 offset:4704
	s_xor_b64 s[26:27], s[24:25], -1
	s_setprio 1
	s_waitcnt lgkmcnt(0)
	v_mfma_f32_32x32x16_bf16 v[64:79], v[48:51], v[80:83], v[32:47]
	v_mov_b64_e32 v[62:63], v[46:47]
	v_mov_b64_e32 v[60:61], v[44:45]
	v_mov_b64_e32 v[58:59], v[42:43]
	v_mov_b64_e32 v[56:57], v[40:41]
	v_mov_b64_e32 v[54:55], v[38:39]
	v_mov_b64_e32 v[52:53], v[36:37]
	v_mov_b64_e32 v[50:51], v[34:35]
	v_mov_b64_e32 v[48:49], v[32:33]
	s_waitcnt lgkmcnt(5)
	s_nop 0
	v_mfma_f32_32x32x16_bf16 v[48:63], v[116:119], v[80:83], v[48:63]
	s_setprio 0
	v_mfma_f32_32x32x16_bf16 v[64:79], v[112:115], v[84:87], v[64:79]
	v_add_u32_e32 v112, s28, v156
	s_waitcnt lgkmcnt(4)
	v_mfma_f32_32x32x16_bf16 v[48:63], v[120:123], v[84:87], v[48:63]
	v_add3_u32 v152, v112, v155, v157
	ds_read_b64_tr_b16 v[132:133], v152 offset:9216
	ds_read_b64_tr_b16 v[134:135], v152 offset:10752
	ds_read_b64_tr_b16 v[130:131], v152 offset:10816
	ds_read_b64_tr_b16 v[128:129], v152 offset:9280
	s_waitcnt lgkmcnt(7)
	v_mfma_f32_32x32x16_bf16 v[64:79], v[124:127], v[88:91], v[64:79]
	ds_read_b64_tr_b16 v[124:125], v152 offset:12288
	ds_read_b64_tr_b16 v[126:127], v152 offset:13824
	ds_read_b64_tr_b16 v[122:123], v152 offset:13888
	ds_read_b64_tr_b16 v[120:121], v152 offset:12352
	ds_read_b64_tr_b16 v[116:117], v152 offset:15360
	ds_read_b64_tr_b16 v[118:119], v152 offset:16896
	ds_read_b64_tr_b16 v[114:115], v152 offset:16960
	ds_read_b64_tr_b16 v[112:113], v152 offset:15424
	s_waitcnt lgkmcnt(13)
	v_mfma_f32_32x32x16_bf16 v[48:63], v[162:165], v[88:91], v[48:63]
	v_mfma_f32_32x32x16_bf16 v[64:79], v[146:149], v[92:95], v[64:79]
	s_waitcnt lgkmcnt(12)
	v_mfma_f32_32x32x16_bf16 v[48:63], v[166:169], v[92:95], v[48:63]
	s_cmp_eq_u32 m0, 1
	s_cbranch_scc0 .Lwd_slow
	s_nop 7
	v_mov_b32_e32 v142, v64
	s_nop 0
	v_mov_b32_e32 v64, v48
	v_mov_b32_e32 v143, v65
	v_mov_b32_e32 v65, v49
	v_mov_b32_e32 v146, v66
	v_mov_b32_e32 v66, v50
	v_mov_b32_e32 v147, v67
	v_mov_b32_e32 v67, v51
	v_mov_b32_e32 v148, v68
	v_mov_b32_e32 v68, v52
	v_mov_b32_e32 v149, v69
	v_mov_b32_e32 v69, v53
	v_mov_b32_e32 v150, v70
	v_mov_b32_e32 v70, v54
	v_mov_b32_e32 v151, v71
	v_mov_b32_e32 v71, v55
	s_branch .Lwd_join
.Lwd_slow:
	v_sub_u32_e32 v142, 0, v159
	v_add_u32_e32 v161, s44, v158
	v_cmp_gt_i32_e32 vcc, 32, v159
	v_max_i32_e32 v142, v159, v142
	s_nop 0
	v_cndmask_b32_e32 v143, v159, v161, vcc
	v_subrev_u32_e32 v143, 32, v143
	v_cmp_gt_u32_e32 vcc, s70, v142
	v_subrev_u32_e32 v146, 33, v159
	v_subrev_u32_e32 v147, 31, v161
	v_cndmask_b32_e32 v142, v203, v64, vcc
	v_cmp_gt_i32_e32 vcc, s70, v143
	v_sub_u32_e32 v143, 1, v159
	s_nop 0
	v_cndmask_b32_e32 v64, v203, v48, vcc
	v_add_u32_e32 v48, -1, v159
	v_max_i32_e32 v143, v48, v143
	v_cmp_gt_i32_e32 vcc, 32, v48
	s_nop 1
	v_cndmask_b32_e32 v48, v146, v147, vcc
	v_cmp_gt_u32_e32 vcc, s70, v143
	v_subrev_u32_e32 v146, 34, v159
	v_subrev_u32_e32 v147, 30, v161
	v_cndmask_b32_e32 v143, v203, v65, vcc
	v_cmp_gt_i32_e32 vcc, s70, v48
	v_add_u32_e32 v48, -2, v159
	s_nop 0
	v_cndmask_b32_e32 v65, v203, v49, vcc
	v_sub_u32_e32 v49, 2, v159
	v_max_i32_e32 v49, v48, v49
	v_cmp_gt_i32_e32 vcc, 32, v48
	s_nop 1
	v_cndmask_b32_e32 v48, v146, v147, vcc
	v_cmp_gt_u32_e32 vcc, s70, v49
	v_sub_u32_e32 v49, 3, v159
	v_subrev_u32_e32 v147, 29, v161
	v_cndmask_b32_e32 v146, v203, v66, vcc
	v_cmp_gt_i32_e32 vcc, s70, v48
	v_add_u32_e32 v48, -3, v159
	v_max_i32_e32 v49, v48, v49
	v_cndmask_b32_e32 v66, v203, v50, vcc
	v_subrev_u32_e32 v50, 35, v159
	v_cmp_gt_i32_e32 vcc, 32, v48
	s_nop 1
	v_cndmask_b32_e32 v48, v50, v147, vcc
	v_cmp_gt_u32_e32 vcc, s70, v49
	v_sub_u32_e32 v49, 8, v159
	v_subrev_u32_e32 v50, 40, v159
	v_cndmask_b32_e32 v147, v203, v67, vcc
	v_cmp_gt_i32_e32 vcc, s70, v48
	v_add_u32_e32 v48, -8, v159
	v_max_i32_e32 v49, v48, v49
	v_cndmask_b32_e32 v67, v203, v51, vcc
	v_subrev_u32_e32 v51, 24, v161
	v_cmp_gt_i32_e32 vcc, 32, v48
	s_nop 1
	v_cndmask_b32_e32 v48, v50, v51, vcc
	v_cmp_gt_u32_e32 vcc, s70, v49
	v_sub_u32_e32 v49, 9, v159
	v_subrev_u32_e32 v50, 41, v159
	v_cndmask_b32_e32 v148, v203, v68, vcc
	v_cmp_gt_i32_e32 vcc, s70, v48
	v_add_u32_e32 v48, -9, v159
	v_max_i32_e32 v49, v48, v49
	v_cndmask_b32_e32 v68, v203, v52, vcc
	v_subrev_u32_e32 v51, 23, v161
; DI float fexp2(float x) { return __builtin_amdgcn_exp2f(x); }
; DI float shx(float v, int m) { return __shfl_xor(v, m, 64); }
; DI float max3f(float a, float b, float c) { float r; asm("v_max3_f32 %0, %1, %2, %3" : "=v"(r) : "v"(a), "v"(b), "v"(c)); return r; }
; template <int DQK, bool WIN>
; DI void attn_run(int wv, const bf16_t* Qrow0, int qs, const bf16_t* Kb, int ks, const bf16_t* Vb, int vs,
;                  int kt0, int kt1, int qpos0, int window, LAS unsigned char* lds, f32x16 (&o)[2], float& m_out, float& l_out) {
;     ...
;             if (WIN) {
;                 const int qp_ = qpos0 + r32, kb_ = 64 * kt + 4 * h;
; #pragma unroll
;                 for (int r = 0; r < 16; ++r) {
;                     const int kk = kb_ + (r & 3) + 8 * (r >> 2);
;                     int d0 = qp_ - kk; d0 = d0 < 0 ? -d0 : d0;
;                     int d1 = qp_ - kk - 32; d1 = d1 < 0 ? -d1 : d1;
;                     if (d0 > window) p0[r] = -1e30f;
;                     if (d1 > window) p1[r] = -1e30f;
;                 }
;             }
;             float mxa = max3f(p0[0], p0[1], p1[0]), mxb = max3f(p0[2], p0[3], p1[1]);
;             mxa = max3f(mxa, p1[2], p1[3]);
; #pragma unroll
;             for (int r = 4; r < 16; r += 4) { mxa = max3f(mxa, p0[r], p0[r + 1]); mxb = max3f(mxb, p0[r + 2], p0[r + 3]); mxa = max3f(mxa, p1[r], p1[r + 1]); mxb = max3f(mxb, p1[r + 2], p1[r + 3]); }
;             float mx = max3f(mxa, mxb, mxb);
;             mx = max3f(mx, shx(mx, 32), mx);
;             if (first || __any(mx > 8.0f)) {
;                 const float d = first ? (WIN ? fmaxf(mx, -1e20f) : mx) : fmaxf(mx, 0.f);
;                 const float alpha = first ? 1.f : fexp2(-d);
	v_cmp_gt_i32_e32 vcc, 32, v48
	s_nop 1
	v_cndmask_b32_e32 v48, v50, v51, vcc
	v_cmp_gt_u32_e32 vcc, s70, v49
	v_sub_u32_e32 v49, 10, v159
	v_subrev_u32_e32 v50, 42, v159
	v_cndmask_b32_e32 v149, v203, v69, vcc
	v_cmp_gt_i32_e32 vcc, s70, v48
	v_add_u32_e32 v48, -10, v159
	v_max_i32_e32 v49, v48, v49
	v_cndmask_b32_e32 v69, v203, v53, vcc
	v_subrev_u32_e32 v51, 22, v161
	v_cmp_gt_i32_e32 vcc, 32, v48
	s_nop 1
	v_cndmask_b32_e32 v48, v50, v51, vcc
	v_cmp_gt_u32_e32 vcc, s70, v49
	v_sub_u32_e32 v49, 11, v159
	v_subrev_u32_e32 v50, 43, v159
	v_cndmask_b32_e32 v150, v203, v70, vcc
	v_cmp_gt_i32_e32 vcc, s70, v48
	v_add_u32_e32 v48, -11, v159
	v_max_i32_e32 v49, v48, v49
	v_cndmask_b32_e32 v70, v203, v54, vcc
	v_subrev_u32_e32 v51, 21, v161
	v_cmp_gt_i32_e32 vcc, 32, v48
	s_nop 1
	v_cndmask_b32_e32 v48, v50, v51, vcc
	v_cmp_gt_u32_e32 vcc, s70, v49
	v_sub_u32_e32 v49, 16, v159
	v_subrev_u32_e32 v50, 48, v159
	v_cndmask_b32_e32 v151, v203, v71, vcc
	v_cmp_gt_i32_e32 vcc, s70, v48
	v_add_u32_e32 v48, -16, v159
	v_max_i32_e32 v49, v48, v49
	v_cndmask_b32_e32 v71, v203, v55, vcc
	v_add_u32_e32 v51, -16, v161
	v_cmp_gt_i32_e32 vcc, 32, v48
	s_nop 1
	v_cndmask_b32_e32 v48, v50, v51, vcc
	v_cmp_gt_u32_e32 vcc, s70, v49
	v_sub_u32_e32 v49, 17, v159
	v_subrev_u32_e32 v50, 49, v159
	v_cndmask_b32_e32 v72, v203, v72, vcc
	v_cmp_gt_i32_e32 vcc, s70, v48
	v_subrev_u32_e32 v48, 17, v159
	v_max_i32_e32 v49, v48, v49
	v_cndmask_b32_e32 v56, v203, v56, vcc
	v_add_u32_e32 v51, -15, v161
	v_cmp_gt_i32_e32 vcc, 32, v48
	s_nop 1
	v_cndmask_b32_e32 v48, v50, v51, vcc
	v_cmp_gt_u32_e32 vcc, s70, v49
	v_sub_u32_e32 v49, 18, v159
	v_subrev_u32_e32 v50, 50, v159
	v_cndmask_b32_e32 v73, v203, v73, vcc
	v_cmp_gt_i32_e32 vcc, s70, v48
	v_subrev_u32_e32 v48, 18, v159
	v_max_i32_e32 v49, v48, v49
	v_cndmask_b32_e32 v57, v203, v57, vcc
	v_add_u32_e32 v51, -14, v161
	v_cmp_gt_i32_e32 vcc, 32, v48
	s_nop 1
	v_cndmask_b32_e32 v48, v50, v51, vcc
	v_cmp_gt_u32_e32 vcc, s70, v49
	v_sub_u32_e32 v49, 19, v159
	v_subrev_u32_e32 v50, 51, v159
	v_cndmask_b32_e32 v74, v203, v74, vcc
	v_cmp_gt_i32_e32 vcc, s70, v48
	v_subrev_u32_e32 v48, 19, v159
	v_max_i32_e32 v49, v48, v49
	v_cndmask_b32_e32 v58, v203, v58, vcc
	v_add_u32_e32 v51, -13, v161
	v_cmp_gt_i32_e32 vcc, 32, v48
	s_nop 1
	v_cndmask_b32_e32 v48, v50, v51, vcc
	v_cmp_gt_u32_e32 vcc, s70, v49
	v_sub_u32_e32 v49, 24, v159
	v_subrev_u32_e32 v50, 56, v159
	v_cndmask_b32_e32 v75, v203, v75, vcc
	v_cmp_gt_i32_e32 vcc, s70, v48
	v_subrev_u32_e32 v48, 24, v159
	v_max_i32_e32 v49, v48, v49
	v_cndmask_b32_e32 v59, v203, v59, vcc
	v_add_u32_e32 v51, -8, v161
	v_cmp_gt_i32_e32 vcc, 32, v48
	s_nop 1
	v_cndmask_b32_e32 v48, v50, v51, vcc
	v_cmp_gt_u32_e32 vcc, s70, v49
	v_sub_u32_e32 v49, 25, v159
	v_subrev_u32_e32 v50, 57, v159
	v_cndmask_b32_e32 v76, v203, v76, vcc
	v_cmp_gt_i32_e32 vcc, s70, v48
	v_subrev_u32_e32 v48, 25, v159
	v_max_i32_e32 v49, v48, v49
	v_cndmask_b32_e32 v60, v203, v60, vcc
	v_add_u32_e32 v51, -7, v161
	v_cmp_gt_i32_e32 vcc, 32, v48
	s_nop 1
	v_cndmask_b32_e32 v48, v50, v51, vcc
	v_cmp_gt_u32_e32 vcc, s70, v49
	v_sub_u32_e32 v49, 26, v159
	v_subrev_u32_e32 v50, 58, v159
	v_cndmask_b32_e32 v77, v203, v77, vcc
	v_cmp_gt_i32_e32 vcc, s70, v48
	v_subrev_u32_e32 v48, 26, v159
	v_max_i32_e32 v49, v48, v49
	v_cndmask_b32_e32 v61, v203, v61, vcc
	v_add_u32_e32 v51, -6, v161
	v_cmp_gt_i32_e32 vcc, 32, v48
	s_nop 1
	v_cndmask_b32_e32 v48, v50, v51, vcc
	v_cmp_gt_u32_e32 vcc, s70, v49
	v_sub_u32_e32 v49, 27, v159
	v_subrev_u32_e32 v50, 59, v159
	v_cndmask_b32_e32 v78, v203, v78, vcc
	v_cmp_gt_i32_e32 vcc, s70, v48
	v_subrev_u32_e32 v48, 27, v159
	v_max_i32_e32 v49, v48, v49
	v_cndmask_b32_e32 v62, v203, v62, vcc
	v_add_u32_e32 v51, -5, v161
	v_cmp_gt_i32_e32 vcc, 32, v48
	s_nop 1
	v_cndmask_b32_e32 v48, v50, v51, vcc
	v_cmp_gt_u32_e32 vcc, s70, v49
	s_nop 1
	v_cndmask_b32_e32 v79, v203, v79, vcc
	v_cmp_gt_i32_e32 vcc, s70, v48
	s_nop 1
	v_cndmask_b32_e32 v63, v203, v63, vcc
.Lwd_join:
	v_max3_f32 v49, v146, v147, v65
	v_max3_f32 v49, v49, v150, v151
	v_max3_f32 v48, v142, v143, v64
	v_max3_f32 v49, v49, v70, v71
	v_max3_f32 v48, v48, v66, v67
	v_max3_f32 v49, v49, v74, v75
	v_max3_f32 v48, v48, v148, v149
	v_max3_f32 v49, v49, v58, v59
	v_cmp_lt_i32_e32 vcc, v202, v197
	v_max3_f32 v48, v48, v68, v69
	v_max3_f32 v49, v49, v78, v79
	v_max3_f32 v48, v48, v72, v73
	v_max3_f32 v49, v49, v62, v63
	v_max3_f32 v48, v48, v56, v57
	v_max3_f32 v48, v48, v76, v77
	v_max3_f32 v48, v48, v60, v61
	v_max3_f32 v161, v48, v49, v49
	v_cndmask_b32_e32 v48, v185, v202, vcc
	v_lshlrev_b32_e32 v48, 2, v48
	ds_bpermute_b32 v162, v48, v161
	ds_read_b64_tr_b16 v[52:53], v152 offset:18432
	ds_read_b64_tr_b16 v[54:55], v152 offset:19968
	ds_read_b64_tr_b16 v[50:51], v152 offset:20032
	ds_read_b64_tr_b16 v[48:49], v152 offset:18496
	s_andn2_b64 vcc, exec, s[26:27]
	s_waitcnt lgkmcnt(4)
	v_max3_f32 v161, v161, v162, v161
	s_cbranch_vccnz .LBB0_1259
	v_cmp_lt_f32_e32 vcc, s71, v161
	s_mov_b64 s[28:29], 0
	s_mov_b64 s[26:27], 0
	s_cbranch_vccz .LBB0_1250
	v_max_f32_e32 v152, v161, v161
	v_max_f32_e32 v152, 0, v152
	s_mov_b64 s[26:27], -1

; DI s16x4 vtr(const LAS unsigned char* p) { return __builtin_bit_cast(s16x4, __builtin_amdgcn_ds_read_tr16_b64_v4i16((LAS s16x4*)p)); }
; template <int DQK, bool WIN>
; DI void attn_run(int wv, const bf16_t* Qrow0, int qs, const bf16_t* Kb, int ks, const bf16_t* Vb, int vs,
;                  int kt0, int kt1, int qpos0, int window, LAS unsigned char* lds, f32x16 (&o)[2], float& m_out, float& l_out) {
;     ...
;             f32x16 p0 = __builtin_amdgcn_mfma_f32_32x32x16_bf16(kf0[0], q[0], negm, 0, 0, 0);
;             f32x16 p1 = __builtin_amdgcn_mfma_f32_32x32x16_bf16(kf1[0], q[0], negm, 0, 0, 0);
; #pragma unroll
;             for (int ds = 1; ds < NDS; ++ds) {
;                 p0 = __builtin_amdgcn_mfma_f32_32x32x16_bf16(kf0[ds], q[ds], p0, 0, 0, 0);
;                 p1 = __builtin_amdgcn_mfma_f32_32x32x16_bf16(kf1[ds], q[ds], p1, 0, 0, 0);
;             }
;             __builtin_amdgcn_s_setprio(0);
;             s16x4 vlo[4][2], vhi[4][2];
; #pragma unroll
;             for (int k4 = 0; k4 < 4; ++k4)
; #pragma unroll
;                 for (int db = 0; db < 2; ++db) {
;                     vlo[k4][db] = vtr(base + vfo + (16 * k4) * VP + 64 * db);
;                     vhi[k4][db] = vtr(base + vfo + (16 * k4 + 8) * VP + 64 * db);
;                 }
;             if (WIN) {
;                 const int qp_ = qpos0 + r32, kb_ = 64 * kt + 4 * h;
; #pragma unroll
;                 for (int r = 0; r < 16; ++r) {
;                     const int kk = kb_ + (r & 3) + 8 * (r >> 2);
;                     int d0 = qp_ - kk; d0 = d0 < 0 ? -d0 : d0;
;                     int d1 = qp_ - kk - 32; d1 = d1 < 0 ? -d1 : d1;
;                     if (d0 > window) p0[r] = -1e30f;
;                     if (d1 > window) p1[r] = -1e30f;
;                 }
.LBB0_1272:
	s_add_i32 s15, s68, -2
	s_add_i32 s36, s12, s13
	s_add_i32 m0, s75, 31
	s_cmp_ge_i32 s36, m0
	s_cselect_b32 m0, 1, 0
	s_sub_i32 vcc_lo, s14, 0x5e
	s_cmp_le_i32 s36, vcc_lo
	s_cselect_b32 vcc_lo, 1, 0
	s_and_b32 m0, m0, vcc_lo
	s_and_b32 s15, s15, 1
	s_add_i32 s30, s36, 63
	s_cmp_ge_i32 s30, s75
	s_cselect_b64 s[30:31], -1, 0
	s_cmp_le_u32 s36, s14
	s_cselect_b64 s[36:37], -1, 0
	s_and_b64 s[30:31], s[30:31], s[36:37]
	s_andn2_b64 vcc, exec, s[30:31]
	s_cbranch_vccnz .LBB0_1281
	s_mul_i32 s30, s15, 0x5400
	s_add_i32 s36, s30, 0
	v_add3_u32 v52, s36, v154, v144
	ds_read_b128 v[48:51], v52
	ds_read_b128 v[112:115], v52 offset:32
	ds_read_b128 v[116:119], v52 offset:4608
	ds_read_b128 v[120:123], v52 offset:4640
	ds_read_b128 v[124:127], v52 offset:64
	ds_read_b128 v[146:149], v52 offset:96
	ds_read_b128 v[162:165], v52 offset:4672
	ds_read_b128 v[166:169], v52 offset:4704
	s_xor_b64 s[30:31], s[28:29], -1
	s_setprio 1
	s_waitcnt lgkmcnt(0)
	v_mfma_f32_32x32x16_bf16 v[64:79], v[48:51], v[80:83], v[32:47]
	v_mov_b64_e32 v[62:63], v[46:47]
	v_mov_b64_e32 v[60:61], v[44:45]
	v_mov_b64_e32 v[58:59], v[42:43]
	v_mov_b64_e32 v[56:57], v[40:41]
	v_mov_b64_e32 v[54:55], v[38:39]
	v_mov_b64_e32 v[52:53], v[36:37]
	v_mov_b64_e32 v[50:51], v[34:35]
	v_mov_b64_e32 v[48:49], v[32:33]
	s_nop 1
	v_mfma_f32_32x32x16_bf16 v[48:63], v[116:119], v[80:83], v[48:63]
	s_setprio 0
	v_mfma_f32_32x32x16_bf16 v[64:79], v[112:115], v[84:87], v[64:79]
	v_add_u32_e32 v112, s36, v156
	v_add3_u32 v152, v112, v155, v157
	v_mfma_f32_32x32x16_bf16 v[48:63], v[120:123], v[84:87], v[48:63]
	v_mfma_f32_32x32x16_bf16 v[64:79], v[124:127], v[88:91], v[64:79]
	ds_read_b64_tr_b16 v[132:133], v152 offset:9216
	ds_read_b64_tr_b16 v[134:135], v152 offset:10752
	ds_read_b64_tr_b16 v[130:131], v152 offset:10816
	ds_read_b64_tr_b16 v[128:129], v152 offset:9280
	ds_read_b64_tr_b16 v[124:125], v152 offset:12288
	ds_read_b64_tr_b16 v[126:127], v152 offset:13824
	ds_read_b64_tr_b16 v[122:123], v152 offset:13888
	ds_read_b64_tr_b16 v[120:121], v152 offset:12352
	ds_read_b64_tr_b16 v[116:117], v152 offset:15360
	ds_read_b64_tr_b16 v[118:119], v152 offset:16896
	ds_read_b64_tr_b16 v[114:115], v152 offset:16960
	ds_read_b64_tr_b16 v[112:113], v152 offset:15424
	v_mfma_f32_32x32x16_bf16 v[48:63], v[162:165], v[88:91], v[48:63]
	v_mfma_f32_32x32x16_bf16 v[64:79], v[146:149], v[92:95], v[64:79]
	v_mfma_f32_32x32x16_bf16 v[48:63], v[166:169], v[92:95], v[48:63]
	s_cmp_eq_u32 m0, 1
	s_cbranch_scc0 .Lwc_slow
	s_nop 8
	v_mov_b32_e32 v142, v64
	v_mov_b32_e32 v64, v48
	v_mov_b32_e32 v143, v65
	v_mov_b32_e32 v65, v49
	v_mov_b32_e32 v146, v66
	v_mov_b32_e32 v66, v50
	v_mov_b32_e32 v147, v67
	v_mov_b32_e32 v67, v51
	v_mov_b32_e32 v148, v68
	v_mov_b32_e32 v68, v52
	v_mov_b32_e32 v149, v69
	v_mov_b32_e32 v69, v53
	v_mov_b32_e32 v150, v70
	v_mov_b32_e32 v70, v54
	v_mov_b32_e32 v151, v71
	v_mov_b32_e32 v71, v55
	s_branch .Lwc_join
.Lwc_slow:
	v_add_u32_e32 v142, 27, v159
	v_sub_u32_e32 v143, 0xffffffe5, v159
	v_add_u32_e32 v161, s12, v158
	v_max_i32_e32 v143, v142, v143
	v_cmp_gt_i32_e32 vcc, 32, v142
	v_add_u32_e32 v146, -5, v159
	v_add_u32_e32 v147, 32, v161
	v_cndmask_b32_e32 v146, v146, v147, vcc
	v_cmp_gt_u32_e32 vcc, s87, v143
	v_sub_u32_e32 v143, 0xffffffe6, v159
	v_add_u32_e32 v147, 33, v161
	v_cndmask_b32_e32 v142, v203, v64, vcc
	v_cmp_gt_i32_e32 vcc, s87, v146
	v_add_u32_e32 v146, -6, v159
	s_nop 0
	v_cndmask_b32_e32 v64, v203, v48, vcc
	v_add_u32_e32 v48, 26, v159
	v_max_i32_e32 v143, v48, v143
	v_cmp_gt_i32_e32 vcc, 32, v48
	s_nop 1
	v_cndmask_b32_e32 v48, v146, v147, vcc
	v_cmp_gt_u32_e32 vcc, s87, v143
	v_add_u32_e32 v146, -7, v159
	v_add_u32_e32 v147, 34, v161
	v_cndmask_b32_e32 v143, v203, v65, vcc
	v_cmp_gt_i32_e32 vcc, s87, v48
	v_add_u32_e32 v48, 25, v159
	s_nop 0
	v_cndmask_b32_e32 v65, v203, v49, vcc
	v_sub_u32_e32 v49, 0xffffffe7, v159
	v_max_i32_e32 v49, v48, v49
	v_cmp_gt_i32_e32 vcc, 32, v48
	s_nop 1
	v_cndmask_b32_e32 v48, v146, v147, vcc
	v_cmp_gt_u32_e32 vcc, s87, v49
	v_sub_u32_e32 v49, 0xffffffe8, v159
	v_add_u32_e32 v147, 35, v161
	v_cndmask_b32_e32 v146, v203, v66, vcc
	v_cmp_gt_i32_e32 vcc, s87, v48
	v_add_u32_e32 v48, 24, v159
	v_max_i32_e32 v49, v48, v49
	v_cndmask_b32_e32 v66, v203, v50, vcc
	v_add_u32_e32 v50, -8, v159
	v_cmp_gt_i32_e32 vcc, 32, v48
	s_nop 1
	v_cndmask_b32_e32 v48, v50, v147, vcc
	v_cmp_gt_u32_e32 vcc, s87, v49
	v_sub_u32_e32 v49, 0xffffffed, v159
	v_add_u32_e32 v50, -13, v159
	v_cndmask_b32_e32 v147, v203, v67, vcc
	v_cmp_gt_i32_e32 vcc, s87, v48
	v_add_u32_e32 v48, 19, v159
	v_max_i32_e32 v49, v48, v49
	v_cndmask_b32_e32 v67, v203, v51, vcc
	v_add_u32_e32 v51, 40, v161
	v_cmp_gt_i32_e32 vcc, 32, v48
	s_nop 1
	v_cndmask_b32_e32 v48, v50, v51, vcc
	v_cmp_gt_u32_e32 vcc, s87, v49
	v_sub_u32_e32 v49, 0xffffffee, v159
	v_add_u32_e32 v50, -14, v159
	v_cndmask_b32_e32 v148, v203, v68, vcc
	v_cmp_gt_i32_e32 vcc, s87, v48
	v_add_u32_e32 v48, 18, v159
	v_max_i32_e32 v49, v48, v49
	v_cndmask_b32_e32 v68, v203, v52, vcc
	v_add_u32_e32 v51, 41, v161
; DI float fexp2(float x) { return __builtin_amdgcn_exp2f(x); }
; DI float shx(float v, int m) { return __shfl_xor(v, m, 64); }
; DI float max3f(float a, float b, float c) { float r; asm("v_max3_f32 %0, %1, %2, %3" : "=v"(r) : "v"(a), "v"(b), "v"(c)); return r; }
; template <int DQK, bool WIN>
; DI void attn_run(int wv, const bf16_t* Qrow0, int qs, const bf16_t* Kb, int ks, const bf16_t* Vb, int vs,
;                  int kt0, int kt1, int qpos0, int window, LAS unsigned char* lds, f32x16 (&o)[2], float& m_out, float& l_out) {
;     ...
;             if (WIN) {
;                 const int qp_ = qpos0 + r32, kb_ = 64 * kt + 4 * h;
; #pragma unroll
;                 for (int r = 0; r < 16; ++r) {
;                     const int kk = kb_ + (r & 3) + 8 * (r >> 2);
;                     int d0 = qp_ - kk; d0 = d0 < 0 ? -d0 : d0;
;                     int d1 = qp_ - kk - 32; d1 = d1 < 0 ? -d1 : d1;
;                     if (d0 > window) p0[r] = -1e30f;
;                     if (d1 > window) p1[r] = -1e30f;
;                 }
;             }
;             float mxa = max3f(p0[0], p0[1], p1[0]), mxb = max3f(p0[2], p0[3], p1[1]);
;             mxa = max3f(mxa, p1[2], p1[3]);
; #pragma unroll
;             for (int r = 4; r < 16; r += 4) { mxa = max3f(mxa, p0[r], p0[r + 1]); mxb = max3f(mxb, p0[r + 2], p0[r + 3]); mxa = max3f(mxa, p1[r], p1[r + 1]); mxb = max3f(mxb, p1[r + 2], p1[r + 3]); }
;             float mx = max3f(mxa, mxb, mxb);
;             mx = max3f(mx, shx(mx, 32), mx);
;             if (first || __any(mx > 8.0f)) {
;                 const float d = first ? (WIN ? fmaxf(mx, -1e20f) : mx) : fmaxf(mx, 0.f);
;                 const float alpha = first ? 1.f : fexp2(-d);
	v_cmp_gt_i32_e32 vcc, 32, v48
	s_nop 1
	v_cndmask_b32_e32 v48, v50, v51, vcc
	v_cmp_gt_u32_e32 vcc, s87, v49
	v_sub_u32_e32 v49, 0xffffffef, v159
	v_add_u32_e32 v50, -15, v159
	v_cndmask_b32_e32 v149, v203, v69, vcc
	v_cmp_gt_i32_e32 vcc, s87, v48
	v_add_u32_e32 v48, 17, v159
	v_max_i32_e32 v49, v48, v49
	v_cndmask_b32_e32 v69, v203, v53, vcc
	v_add_u32_e32 v51, 42, v161
	v_cmp_gt_i32_e32 vcc, 32, v48
	s_nop 1
	v_cndmask_b32_e32 v48, v50, v51, vcc
	v_cmp_gt_u32_e32 vcc, s87, v49
	v_sub_u32_e32 v49, -16, v159
	v_add_u32_e32 v50, -16, v159
	v_cndmask_b32_e32 v150, v203, v70, vcc
	v_cmp_gt_i32_e32 vcc, s87, v48
	v_add_u32_e32 v48, 16, v159
	v_max_i32_e32 v49, v48, v49
	v_cndmask_b32_e32 v70, v203, v54, vcc
	v_add_u32_e32 v51, 43, v161
	v_cmp_gt_i32_e32 vcc, 32, v48
	s_nop 1
	v_cndmask_b32_e32 v48, v50, v51, vcc
	v_cmp_gt_u32_e32 vcc, s87, v49
	v_sub_u32_e32 v49, -11, v159
	v_subrev_u32_e32 v50, 21, v159
	v_cndmask_b32_e32 v151, v203, v71, vcc
	v_cmp_gt_i32_e32 vcc, s87, v48
	v_add_u32_e32 v48, 11, v159
	v_max_i32_e32 v49, v48, v49
	v_cndmask_b32_e32 v71, v203, v55, vcc
	v_add_u32_e32 v51, 48, v161
	v_cmp_gt_i32_e32 vcc, 32, v48
	s_nop 1
	v_cndmask_b32_e32 v48, v50, v51, vcc
	v_cmp_gt_u32_e32 vcc, s87, v49
	v_sub_u32_e32 v49, -10, v159
	v_subrev_u32_e32 v50, 22, v159
	v_cndmask_b32_e32 v72, v203, v72, vcc
	v_cmp_gt_i32_e32 vcc, s87, v48
	v_add_u32_e32 v48, 10, v159
	v_max_i32_e32 v49, v48, v49
	v_cndmask_b32_e32 v56, v203, v56, vcc
	v_add_u32_e32 v51, 49, v161
	v_cmp_gt_i32_e32 vcc, 32, v48
	s_nop 1
	v_cndmask_b32_e32 v48, v50, v51, vcc
	v_cmp_gt_u32_e32 vcc, s87, v49
	v_sub_u32_e32 v49, -9, v159
	v_subrev_u32_e32 v50, 23, v159
	v_cndmask_b32_e32 v73, v203, v73, vcc
	v_cmp_gt_i32_e32 vcc, s87, v48
	v_add_u32_e32 v48, 9, v159
	v_max_i32_e32 v49, v48, v49
	v_cndmask_b32_e32 v57, v203, v57, vcc
	v_add_u32_e32 v51, 50, v161
	v_cmp_gt_i32_e32 vcc, 32, v48
	s_nop 1
	v_cndmask_b32_e32 v48, v50, v51, vcc
	v_cmp_gt_u32_e32 vcc, s87, v49
	v_sub_u32_e32 v49, -8, v159
	v_subrev_u32_e32 v50, 24, v159
	v_cndmask_b32_e32 v74, v203, v74, vcc
	v_cmp_gt_i32_e32 vcc, s87, v48
	v_add_u32_e32 v48, 8, v159
	v_max_i32_e32 v49, v48, v49
	v_cndmask_b32_e32 v58, v203, v58, vcc
	v_add_u32_e32 v51, 51, v161
	v_cmp_gt_i32_e32 vcc, 32, v48
	s_nop 1
	v_cndmask_b32_e32 v48, v50, v51, vcc
	v_cmp_gt_u32_e32 vcc, s87, v49
	v_sub_u32_e32 v49, -3, v159
	v_subrev_u32_e32 v50, 29, v159
	v_cndmask_b32_e32 v75, v203, v75, vcc
	v_cmp_gt_i32_e32 vcc, s87, v48
	v_add_u32_e32 v48, 3, v159
	v_max_i32_e32 v49, v48, v49
	v_cndmask_b32_e32 v59, v203, v59, vcc
	v_add_u32_e32 v51, 56, v161
	v_cmp_gt_i32_e32 vcc, 32, v48
	s_nop 1
	v_cndmask_b32_e32 v48, v50, v51, vcc
	v_cmp_gt_u32_e32 vcc, s87, v49
	v_sub_u32_e32 v49, -2, v159
	v_subrev_u32_e32 v50, 30, v159
	v_cndmask_b32_e32 v76, v203, v76, vcc
	v_cmp_gt_i32_e32 vcc, s87, v48
	v_add_u32_e32 v48, 2, v159
	v_max_i32_e32 v49, v48, v49
	v_cndmask_b32_e32 v60, v203, v60, vcc
	v_add_u32_e32 v51, 57, v161
	v_cmp_gt_i32_e32 vcc, 32, v48
	s_nop 1
	v_cndmask_b32_e32 v48, v50, v51, vcc
	v_cmp_gt_u32_e32 vcc, s87, v49
	v_not_b32_e32 v49, v159
	v_subrev_u32_e32 v50, 31, v159
	v_cndmask_b32_e32 v77, v203, v77, vcc
	v_cmp_gt_i32_e32 vcc, s87, v48
	v_add_u32_e32 v48, 1, v159
	v_max_i32_e32 v49, v48, v49
	v_cndmask_b32_e32 v61, v203, v61, vcc
	v_add_u32_e32 v51, 58, v161
	v_cmp_gt_i32_e32 vcc, 32, v48
	s_nop 1
	v_cndmask_b32_e32 v48, v50, v51, vcc
	v_cmp_gt_u32_e32 vcc, s87, v49
	v_subrev_u32_e32 v49, 32, v159
	v_add_u32_e32 v50, 59, v161
	v_cndmask_b32_e32 v78, v203, v78, vcc
	v_cmp_gt_i32_e32 vcc, s87, v48
	v_sub_u32_e32 v48, 0, v159
	v_max_i32_e32 v48, v159, v48
	v_cndmask_b32_e32 v62, v203, v62, vcc
	v_cmp_gt_i32_e32 vcc, 32, v159
	s_nop 1
	v_cndmask_b32_e32 v49, v49, v50, vcc
	v_cmp_gt_u32_e32 vcc, s87, v48
	s_nop 1
	v_cndmask_b32_e32 v79, v203, v79, vcc
	v_cmp_gt_i32_e32 vcc, s87, v49
	s_nop 1
	v_cndmask_b32_e32 v63, v203, v63, vcc
.Lwc_join:
	v_max3_f32 v48, v142, v143, v64
	v_max3_f32 v48, v48, v66, v67
	v_max3_f32 v49, v146, v147, v65
	v_max3_f32 v48, v48, v148, v149
	v_max3_f32 v49, v49, v150, v151
	v_max3_f32 v48, v48, v68, v69
	v_max3_f32 v49, v49, v70, v71
	v_max3_f32 v48, v48, v72, v73
	v_cmp_lt_i32_e32 vcc, v202, v197
	v_max3_f32 v49, v49, v74, v75
	v_max3_f32 v48, v48, v56, v57
	v_max3_f32 v49, v49, v58, v59
	v_max3_f32 v48, v48, v76, v77
	v_max3_f32 v49, v49, v78, v79
	v_max3_f32 v48, v48, v60, v61
	v_max3_f32 v49, v49, v62, v63
	v_max3_f32 v161, v48, v49, v49
	v_cndmask_b32_e32 v48, v185, v202, vcc
	v_lshlrev_b32_e32 v48, 2, v48
	ds_bpermute_b32 v162, v48, v161
	ds_read_b64_tr_b16 v[52:53], v152 offset:18432
	ds_read_b64_tr_b16 v[54:55], v152 offset:19968
	ds_read_b64_tr_b16 v[50:51], v152 offset:20032
	ds_read_b64_tr_b16 v[48:49], v152 offset:18496
	s_andn2_b64 vcc, exec, s[30:31]
	s_waitcnt lgkmcnt(4)
	v_max3_f32 v161, v161, v162, v161
	s_cbranch_vccnz .LBB0_1285
	v_cmp_lt_f32_e32 vcc, s71, v161
	s_mov_b64 s[54:55], 0
	s_mov_b64 s[30:31], 0
	s_cbranch_vccz .LBB0_1276
	v_max_f32_e32 v152, v161, v161
	v_max_f32_e32 v152, 0, v152
	s_mov_b64 s[30:31], -1
